# tile headers: group-height divide replaced by shift/mask (always 4), GEMM1 accumulator-clear MFMAs interleaved with the scalar index code
# speedup vs baseline: 1.0053x; 1.0035x over previous
.LBB0_137:
	v_mov_b32_e32 v228, 0
	v_mov_b32_e32 v229, 0
	v_mov_b32_e32 v230, 0
	v_mov_b32_e32 v231, 0
	v_readlane_b32 s48, v251, 1
	s_add_i32 s29, s29, 1
	v_readlane_b32 s21, v251, 22
	v_readlane_b32 s50, v251, 3
	v_mfma_f32_32x32x16_bf16 v[16:31], v[228:231], v[228:231], 0
	s_mul_i32 s21, s29, s21
	s_mul_hi_u32 s23, s29, s50
	s_add_i32 s23, s23, s21
	s_mul_i32 s21, s29, s50
	v_mfma_f32_32x32x16_bf16 v[32:47], v[228:231], v[228:231], 0
	v_readlane_b32 s24, v251, 0
	s_add_u32 s24, s21, s24
	v_readlane_b32 s21, v251, 21
	s_addc_u32 s25, s23, s21
	v_mfma_f32_32x32x16_bf16 v[48:63], v[228:231], v[228:231], 0
	v_cmp_ge_i64_e32 vcc, s[24:25], v[164:165]
	v_cmp_lt_i64_e64 s[42:43], s[24:25], v[164:165]
	v_readlane_b32 s49, v251, 2
	v_readlane_b32 s51, v251, 4
	v_mfma_f32_32x32x16_bf16 v[64:79], v[228:231], v[228:231], 0
	s_cbranch_vccnz .LBB0_139
	s_ashr_i32 s20, s24, 31
	s_lshr_b32 s20, s20, 29
	s_add_i32 s20, s24, s20
	s_ashr_i32 s21, s20, 3
	s_and_b32 s20, s20, -8
	s_sub_i32 s20, s24, s20
	s_cmp_lt_i32 s20, 0
	s_cselect_b32 s22, s3, s2
	s_mul_i32 s20, s22, s20
	s_add_i32 s20, s20, s21
	s_abs_i32 s22, s20
	s_mul_hi_u32 s23, s22, s11
	s_mul_i32 s24, s23, s9
	s_sub_i32 s22, s22, s24
	s_ashr_i32 s21, s20, 31
	s_add_i32 s24, s23, 1
	s_sub_i32 s25, s22, s9
	s_cmp_ge_u32 s22, s9
	s_cselect_b32 s23, s24, s23
	s_cselect_b32 s22, s25, s22
	s_add_i32 s24, s23, 1
	s_cmp_ge_u32 s22, s9
	s_cselect_b32 s22, s24, s23
	s_xor_b32 s22, s22, s21
	s_sub_i32 s21, s22, s21
	s_lshl_b32 s22, s21, 2
	s_mul_i32 s21, s21, s9
	s_sub_i32 s21, s20, s21
	s_lshr_b32 s20, s21, 2
	s_and_b32 s21, s21, 3
	s_add_i32 s22, s21, s22
.LBB0_139:
	s_ashr_i32 s23, s22, 31
	s_lshl_b64 s[24:25], s[22:23], 19
	s_add_u32 s24, s80, s24
	s_addc_u32 s25, s81, s25
	v_mfma_f32_32x32x16_bf16 v[80:95], v[228:231], v[228:231], 0
	s_and_b64 s[30:31], s[42:43], exec
	s_cselect_b32 s23, s25, s41
	s_cselect_b32 s35, s24, s40
	s_ashr_i32 s21, s20, 31
	v_mfma_f32_32x32x16_bf16 v[96:111], v[228:231], v[228:231], 0
	s_lshl_b64 s[30:31], s[20:21], 19
	s_add_u32 s30, s6, s30
	s_addc_u32 s31, s7, s31
	s_and_b64 s[46:47], s[42:43], exec
	v_mfma_f32_32x32x16_bf16 v[112:127], v[228:231], v[228:231], 0
	s_cselect_b32 s21, s31, s45
	s_cselect_b32 s36, s30, s44
	s_add_u32 s40, s40, 0x40080
	s_addc_u32 s41, s41, 0
	v_mfma_f32_32x32x16_bf16 v[0:15], v[228:231], v[228:231], 0
	s_add_u32 s48, s44, 0x100
	s_addc_u32 s49, s45, 0
	s_mov_b32 s50, -2
	s_cmp_lg_u32 s29, 1
	s_cbranch_scc1 .Lfw_0
	s_waitcnt vmcnt(6)
	s_barrier

.LBB0_409:
	v_readlane_b32 s48, v251, 1
	s_add_i32 s33, s33, 1
	v_readlane_b32 s8, v251, 22
	v_readlane_b32 s50, v251, 3
	s_mul_i32 s8, s33, s8
	s_mul_hi_u32 s9, s33, s50
	s_add_i32 s9, s9, s8
	s_mul_i32 s8, s33, s50
	v_readlane_b32 s48, v251, 0
	s_add_u32 s8, s8, s48
	v_readlane_b32 s48, v251, 21
	s_addc_u32 s9, s9, s48
	v_mov_b64_e32 v[0:1], s[76:77]
	v_readlane_b32 s51, v251, 4
	v_cmp_ge_i64_e32 vcc, s[8:9], v[0:1]
	v_cmp_lt_i64_e64 s[50:51], s[8:9], v[0:1]
	v_readlane_b32 s49, v251, 2
	s_cbranch_vccnz .LBB0_411
	s_ashr_i32 s9, s8, 31
	s_lshr_b32 s9, s9, 29
	s_add_i32 s9, s8, s9
	s_ashr_i32 s13, s9, 3
	s_and_b32 s9, s9, -8
	s_sub_i32 s8, s8, s9
	s_lshr_b32 s9, s8, 31
	s_or_b32 s9, s2, s9
	s_mul_i32 s8, s9, s8
	s_add_i32 s8, s8, s13
	s_abs_i32 s13, s8
	s_mul_hi_u32 s48, s13, s94
	s_mul_i32 s49, s48, s93
	s_sub_i32 s13, s13, s49
	s_ashr_i32 s9, s8, 31
	s_add_i32 s49, s48, 1
	s_sub_i32 s56, s13, s93
	s_cmp_ge_u32 s13, s93
	s_cselect_b32 s48, s49, s48
	s_cselect_b32 s13, s56, s13
	s_add_i32 s49, s48, 1
	s_cmp_ge_u32 s13, s93
	s_cselect_b32 s13, s49, s48
	s_xor_b32 s13, s13, s9
	s_sub_i32 s9, s13, s9
	s_lshl_b32 s48, s9, 2
	s_mul_i32 s9, s9, s93
	s_sub_i32 s8, s8, s9
	s_lshr_b32 s13, s8, 2
	s_and_b32 s8, s8, 3
	s_add_i32 s78, s8, s48

.LBB0_849:
	s_ashr_i32 s13, s13, 3
	s_add_i32 s13, s31, s13
	s_ashr_i32 s24, s13, 31
	s_lshr_b32 s24, s24, 28
	s_add_i32 s24, s13, s24
	s_ashr_i32 s25, s24, 4
	s_lshl_b32 s25, s25, 2
	s_and_b32 s24, s24, -16
	s_sub_i32 s24, s13, s24
	s_lshr_b32 s13, s24, 2
	s_and_b32 s24, s24, 3
	s_add_i32 s50, s25, s24
